# dense loop: K/V staging writes and next-tile global loads moved after the first QK MFMA chain (less exposure to global-load latency)
# speedup vs baseline: 1.0525x; 1.0034x over previous
; template <int DV, int NK, int MODE, bool FIXM, int GRP>
; DI void attn_job(char* lds_wg, const AttnJob& J) {
;     ...
;       if (FIXM) {
;         const float nm = -J.m_init;
; #pragma unroll
;         for (int i = 0; i < 16; ++i) { sA[i] = __builtin_amdgcn_exp2f(fmaf(sA[i], C, nm)); sB[i] = __builtin_amdgcn_exp2f(fmaf(sB[i], C, nm)); l += sA[i] + sB[i]; }
;       } else {
;       float mx = sA[0];
; #pragma unroll
;       for (int i = 1; i < 16; ++i) mx = fmaxf(mx, sA[i]);
; #pragma unroll
;       for (int i = 0; i < 16; ++i) mx = fmaxf(mx, sB[i]);
;       mx = swapmax(mx);
;       const float mn = fmaxf(m, mx * C);
;       const float alpha = __builtin_amdgcn_exp2f(m - mn);
;       m = mn;
;       float ps = 0.f;
; #pragma unroll
;       for (int i = 0; i < 16; ++i) { sA[i] = __builtin_amdgcn_exp2f(fmaf(sA[i], C, -mn)); sB[i] = __builtin_amdgcn_exp2f(fmaf(sB[i], C, -mn)); ps += sA[i] + sB[i]; }
;       l = l * alpha + ps;
; #pragma unroll
;       for (int d = 0; d < NDV; ++d)
; #pragma unroll
;         for (int i = 0; i < 16; ++i) O[d][i] *= alpha;
;       }
;       bf16x8 pf[4];
;       { u32x4 w;
;         w.x = cvtpk(sA[0], sA[1]); w.y = cvtpk(sA[2], sA[3]); w.z = cvtpk(sA[4], sA[5]); w.w = cvtpk(sA[6], sA[7]); pf[0] = __builtin_bit_cast(bf16x8, w);
;         w.x = cvtpk(sA[8], sA[9]); w.y = cvtpk(sA[10], sA[11]); w.z = cvtpk(sA[12], sA[13]); w.w = cvtpk(sA[14], sA[15]); pf[1] = __builtin_bit_cast(bf16x8, w);
;         w.x = cvtpk(sB[0], sB[1]); w.y = cvtpk(sB[2], sB[3]); w.z = cvtpk(sB[4], sB[5]); w.w = cvtpk(sB[6], sB[7]); pf[2] = __builtin_bit_cast(bf16x8, w);
;         w.x = cvtpk(sB[8], sB[9]); w.y = cvtpk(sB[10], sB[11]); w.z = cvtpk(sB[12], sB[13]); w.w = cvtpk(sB[14], sB[15]); pf[3] = __builtin_bit_cast(bf16x8, w); }
;       const char* Vl = lds + stage * 32768 + NK * 8192 + vrd;
;       if (FIXM) {
;         bf16x8 vf[4][NDV];
; #pragma unroll
;         for (int ks = 0; ks < 4; ++ks) {
; #pragma unroll
;           for (int d = 0; d < NDV; ++d) {
;             const s16x4 lo = __builtin_amdgcn_ds_read_tr16_b64_v4i16((LAS s16x4*)(Vl + ks * 2 * NDV * 512 + d * 512));
;             const s16x4 hi = __builtin_amdgcn_ds_read_tr16_b64_v4i16((LAS s16x4*)(Vl + ks * 2 * NDV * 512 + d * 512 + 256));
;             vf[ks][d] = __builtin_shufflevector(lo, hi, 0, 1, 2, 3, 4, 5, 6, 7);
;           }
;         }
; #pragma unroll
.Lds0_loop:
	ds_read_b128 v[106:109], v0 offset:16384
	ds_read_b128 v[110:113], v102 offset:16384
	ds_read_b128 v[120:123], v103 offset:16384
	ds_read_b128 v[124:127], v104 offset:16384
	ds_read_b64_tr_b16 v[168:169], v98 offset:8192
	ds_read_b64_tr_b16 v[170:171], v98 offset:8448
	ds_read_b64_tr_b16 v[172:173], v98 offset:8704
	ds_read_b64_tr_b16 v[174:175], v98 offset:8960
	ds_read_b64_tr_b16 v[176:177], v98 offset:10240
	ds_read_b64_tr_b16 v[178:179], v98 offset:10496
	ds_read_b64_tr_b16 v[180:181], v98 offset:10752
	ds_read_b64_tr_b16 v[182:183], v98 offset:11008
	v_exp_f32_e32 v50, v50
	v_exp_f32_e32 v51, v51
	v_exp_f32_e32 v52, v52
	v_exp_f32_e32 v53, v53
	v_exp_f32_e32 v54, v54
	v_exp_f32_e32 v55, v55
	v_exp_f32_e32 v56, v56
	v_exp_f32_e32 v57, v57
	s_waitcnt lgkmcnt(11)
	v_mfma_f32_32x32x16_bf16 v[136:151], v[106:109], v[66:69], 0
	v_cvt_pk_bf16_f32 v152, v50, v51
	v_cvt_pk_bf16_f32 v153, v52, v53
	v_cvt_pk_bf16_f32 v154, v54, v55
	v_cvt_pk_bf16_f32 v155, v56, v57
	v_add_f32_e32 v115, v50, v115
	v_add_f32_e32 v115, v51, v115
	s_waitcnt lgkmcnt(10)
	v_mfma_f32_32x32x16_bf16 v[136:151], v[110:113], v[70:73], v[136:151]
	v_exp_f32_e32 v58, v58
	v_exp_f32_e32 v59, v59
	v_exp_f32_e32 v60, v60
	v_exp_f32_e32 v61, v61
	v_add_f32_e32 v164, v52, v164
	v_add_f32_e32 v164, v53, v164
	s_waitcnt lgkmcnt(9)
	v_mfma_f32_32x32x16_bf16 v[136:151], v[120:123], v[74:77], v[136:151]
	v_exp_f32_e32 v62, v62
	v_exp_f32_e32 v63, v63
	v_exp_f32_e32 v64, v64
	v_exp_f32_e32 v65, v65
	v_add_f32_e32 v115, v54, v115
	v_add_f32_e32 v115, v55, v115
	s_waitcnt lgkmcnt(8)
	v_mfma_f32_32x32x16_bf16 v[136:151], v[124:127], v[78:81], v[136:151]
	ds_read_b128 v[106:109], v0 offset:20480
	ds_read_b128 v[110:113], v102 offset:20480
	ds_read_b128 v[120:123], v103 offset:20480
	ds_read_b128 v[124:127], v104 offset:20480
	s_waitcnt vmcnt(0)
	ds_write_b128 v100, v[82:85] offset:32768
	ds_write_b128 v165, v[86:89] offset:40960
	s_add_i32 s39, s38, 3
	s_cmp_lt_u32 s39, s96
	s_cbranch_scc0 .Lds0_sk0
	global_load_dwordx4 v[82:85], v[92:93], off offset:1024
	global_load_dwordx4 v[86:89], v[90:91], off offset:1280
	v_lshl_add_u64 v[92:93], v[92:93], 0, s[70:71]
	v_lshl_add_u64 v[90:91], v[90:91], 0, s[70:71]
.Lds0_sk0:
	v_add_f32_e32 v164, v56, v164
	v_add_f32_e32 v164, v57, v164
	s_waitcnt lgkmcnt(12)
	v_mfma_f32_32x32x16_bf16 v[18:33], v[168:171], v[152:155], v[18:33]
	v_cvt_pk_bf16_f32 v156, v58, v59
	v_cvt_pk_bf16_f32 v157, v60, v61
	v_cvt_pk_bf16_f32 v158, v62, v63
	v_cvt_pk_bf16_f32 v159, v64, v65
	v_add_f32_e32 v115, v58, v115
	v_add_f32_e32 v115, v59, v115
	s_waitcnt lgkmcnt(10)
	v_mfma_f32_32x32x16_bf16 v[2:17], v[172:175], v[152:155], v[2:17]
	v_add_f32_e32 v164, v60, v164
	v_add_f32_e32 v164, v61, v164
	v_add_f32_e32 v164, v62, v164
	v_add_f32_e32 v164, v63, v164
	v_add_f32_e32 v164, v64, v164
	v_add_f32_e32 v164, v65, v164
	s_waitcnt lgkmcnt(8)
	v_mfma_f32_32x32x16_bf16 v[18:33], v[176:179], v[156:159], v[18:33]
	v_exp_f32_e32 v34, v34
	v_exp_f32_e32 v35, v35
	v_exp_f32_e32 v36, v36
	v_exp_f32_e32 v37, v37
	s_waitcnt lgkmcnt(6)
	v_mfma_f32_32x32x16_bf16 v[2:17], v[180:183], v[156:159], v[2:17]
	ds_read_b64_tr_b16 v[168:169], v98 offset:12288
	ds_read_b64_tr_b16 v[170:171], v98 offset:12544
	ds_read_b64_tr_b16 v[172:173], v98 offset:12800
	ds_read_b64_tr_b16 v[174:175], v98 offset:13056
	ds_read_b64_tr_b16 v[176:177], v98 offset:14336
	ds_read_b64_tr_b16 v[178:179], v98 offset:14592
	ds_read_b64_tr_b16 v[180:181], v98 offset:14848
	ds_read_b64_tr_b16 v[182:183], v98 offset:15104
	v_exp_f32_e32 v38, v38
	v_exp_f32_e32 v39, v39
	v_exp_f32_e32 v40, v40
	v_exp_f32_e32 v41, v41
	s_waitcnt lgkmcnt(13)
	v_mfma_f32_32x32x16_bf16 v[50:65], v[106:109], v[66:69], 0
	v_cvt_pk_bf16_f32 v160, v34, v35
	v_cvt_pk_bf16_f32 v161, v36, v37
	v_cvt_pk_bf16_f32 v162, v38, v39
	v_cvt_pk_bf16_f32 v163, v40, v41
	v_add_f32_e32 v115, v34, v115
	v_add_f32_e32 v115, v35, v115
	s_waitcnt lgkmcnt(12)
	v_mfma_f32_32x32x16_bf16 v[50:65], v[110:113], v[70:73], v[50:65]
	v_exp_f32_e32 v42, v42
	v_exp_f32_e32 v43, v43
	v_exp_f32_e32 v44, v44
	v_exp_f32_e32 v45, v45
	v_add_f32_e32 v164, v36, v164
	v_add_f32_e32 v164, v37, v164
	s_waitcnt lgkmcnt(11)
	v_mfma_f32_32x32x16_bf16 v[50:65], v[120:123], v[74:77], v[50:65]
	v_exp_f32_e32 v46, v46
	v_exp_f32_e32 v47, v47
	v_exp_f32_e32 v48, v48
	v_exp_f32_e32 v49, v49
	v_add_f32_e32 v115, v38, v115
	v_add_f32_e32 v115, v39, v115
	s_waitcnt lgkmcnt(10)
	v_mfma_f32_32x32x16_bf16 v[50:65], v[124:127], v[78:81], v[50:65]
	v_cvt_pk_bf16_f32 v184, v42, v43
	v_cvt_pk_bf16_f32 v185, v44, v45
	v_cvt_pk_bf16_f32 v186, v46, v47
	v_cvt_pk_bf16_f32 v187, v48, v49
	v_add_f32_e32 v164, v40, v164
	v_add_f32_e32 v164, v41, v164
	s_waitcnt lgkmcnt(6)
	v_mfma_f32_32x32x16_bf16 v[18:33], v[168:171], v[160:163], v[18:33]
	v_add_f32_e32 v115, v42, v115
	v_add_f32_e32 v115, v43, v115
	v_add_f32_e32 v115, v44, v115
	v_add_f32_e32 v115, v45, v115
	s_waitcnt lgkmcnt(4)
	v_mfma_f32_32x32x16_bf16 v[2:17], v[172:175], v[160:163], v[2:17]
	v_add_f32_e32 v164, v46, v164
	v_add_f32_e32 v164, v47, v164
	v_add_f32_e32 v164, v48, v164
	v_add_f32_e32 v164, v49, v164
	s_waitcnt lgkmcnt(2)
	v_mfma_f32_32x32x16_bf16 v[18:33], v[176:179], v[184:187], v[18:33]
	s_waitcnt lgkmcnt(0)
	v_mfma_f32_32x32x16_bf16 v[2:17], v[180:183], v[184:187], v[2:17]
	s_waitcnt lgkmcnt(0)
	s_barrier
	s_add_i32 s38, s38, 1
	s_cmp_ge_u32 s38, s96
	s_cbranch_scc1 .Lds0_done
; template <int DV, int NK, int MODE, bool FIXM, int GRP>
; DI void attn_job(char* lds_wg, const AttnJob& J) {
;     ...
;       if (FIXM) {
;         const float nm = -J.m_init;
; #pragma unroll
;         for (int i = 0; i < 16; ++i) { sA[i] = __builtin_amdgcn_exp2f(fmaf(sA[i], C, nm)); sB[i] = __builtin_amdgcn_exp2f(fmaf(sB[i], C, nm)); l += sA[i] + sB[i]; }
;       } else {
;       float mx = sA[0];
; #pragma unroll
;       for (int i = 1; i < 16; ++i) mx = fmaxf(mx, sA[i]);
; #pragma unroll
;       for (int i = 0; i < 16; ++i) mx = fmaxf(mx, sB[i]);
;       mx = swapmax(mx);
;       const float mn = fmaxf(m, mx * C);
;       const float alpha = __builtin_amdgcn_exp2f(m - mn);
;       m = mn;
;       float ps = 0.f;
; #pragma unroll
;       for (int i = 0; i < 16; ++i) { sA[i] = __builtin_amdgcn_exp2f(fmaf(sA[i], C, -mn)); sB[i] = __builtin_amdgcn_exp2f(fmaf(sB[i], C, -mn)); ps += sA[i] + sB[i]; }
;       l = l * alpha + ps;
; #pragma unroll
;       for (int d = 0; d < NDV; ++d)
; #pragma unroll
;         for (int i = 0; i < 16; ++i) O[d][i] *= alpha;
;       }
;       bf16x8 pf[4];
;       { u32x4 w;
;         w.x = cvtpk(sA[0], sA[1]); w.y = cvtpk(sA[2], sA[3]); w.z = cvtpk(sA[4], sA[5]); w.w = cvtpk(sA[6], sA[7]); pf[0] = __builtin_bit_cast(bf16x8, w);
;         w.x = cvtpk(sA[8], sA[9]); w.y = cvtpk(sA[10], sA[11]); w.z = cvtpk(sA[12], sA[13]); w.w = cvtpk(sA[14], sA[15]); pf[1] = __builtin_bit_cast(bf16x8, w);
;         w.x = cvtpk(sB[0], sB[1]); w.y = cvtpk(sB[2], sB[3]); w.z = cvtpk(sB[4], sB[5]); w.w = cvtpk(sB[6], sB[7]); pf[2] = __builtin_bit_cast(bf16x8, w);
;         w.x = cvtpk(sB[8], sB[9]); w.y = cvtpk(sB[10], sB[11]); w.z = cvtpk(sB[12], sB[13]); w.w = cvtpk(sB[14], sB[15]); pf[3] = __builtin_bit_cast(bf16x8, w); }
;       const char* Vl = lds + stage * 32768 + NK * 8192 + vrd;
;       if (FIXM) {
;         bf16x8 vf[4][NDV];
; #pragma unroll
;         for (int ks = 0; ks < 4; ++ks) {
; #pragma unroll
;           for (int d = 0; d < NDV; ++d) {
;             const s16x4 lo = __builtin_amdgcn_ds_read_tr16_b64_v4i16((LAS s16x4*)(Vl + ks * 2 * NDV * 512 + d * 512));
;             const s16x4 hi = __builtin_amdgcn_ds_read_tr16_b64_v4i16((LAS s16x4*)(Vl + ks * 2 * NDV * 512 + d * 512 + 256));
;             vf[ks][d] = __builtin_shufflevector(lo, hi, 0, 1, 2, 3, 4, 5, 6, 7);
;           }
;         }
; #pragma unroll
	ds_read_b128 v[106:109], v0 offset:32768
	ds_read_b128 v[110:113], v102 offset:32768
	ds_read_b128 v[120:123], v103 offset:32768
	ds_read_b128 v[124:127], v104 offset:32768
	ds_read_b64_tr_b16 v[168:169], v98 offset:24576
	ds_read_b64_tr_b16 v[170:171], v98 offset:24832
	ds_read_b64_tr_b16 v[172:173], v98 offset:25088
	ds_read_b64_tr_b16 v[174:175], v98 offset:25344
	ds_read_b64_tr_b16 v[176:177], v98 offset:26624
	ds_read_b64_tr_b16 v[178:179], v98 offset:26880
	ds_read_b64_tr_b16 v[180:181], v98 offset:27136
	ds_read_b64_tr_b16 v[182:183], v98 offset:27392
	v_exp_f32_e32 v136, v136
	v_exp_f32_e32 v137, v137
	v_exp_f32_e32 v138, v138
	v_exp_f32_e32 v139, v139
	v_exp_f32_e32 v140, v140
	v_exp_f32_e32 v141, v141
	v_exp_f32_e32 v142, v142
	v_exp_f32_e32 v143, v143
	s_waitcnt lgkmcnt(11)
	v_mfma_f32_32x32x16_bf16 v[34:49], v[106:109], v[66:69], 0
	v_cvt_pk_bf16_f32 v152, v136, v137
	v_cvt_pk_bf16_f32 v153, v138, v139
	v_cvt_pk_bf16_f32 v154, v140, v141
	v_cvt_pk_bf16_f32 v155, v142, v143
	v_add_f32_e32 v115, v136, v115
	v_add_f32_e32 v115, v137, v115
	s_waitcnt lgkmcnt(10)
	v_mfma_f32_32x32x16_bf16 v[34:49], v[110:113], v[70:73], v[34:49]
	v_exp_f32_e32 v144, v144
	v_exp_f32_e32 v145, v145
	v_exp_f32_e32 v146, v146
	v_exp_f32_e32 v147, v147
	v_add_f32_e32 v164, v138, v164
	v_add_f32_e32 v164, v139, v164
	s_waitcnt lgkmcnt(9)
	v_mfma_f32_32x32x16_bf16 v[34:49], v[120:123], v[74:77], v[34:49]
	v_exp_f32_e32 v148, v148
	v_exp_f32_e32 v149, v149
	v_exp_f32_e32 v150, v150
	v_exp_f32_e32 v151, v151
	v_add_f32_e32 v115, v140, v115
	v_add_f32_e32 v115, v141, v115
	s_waitcnt lgkmcnt(8)
	v_mfma_f32_32x32x16_bf16 v[34:49], v[124:127], v[78:81], v[34:49]
	ds_read_b128 v[106:109], v0 offset:36864
	ds_read_b128 v[110:113], v102 offset:36864
	ds_read_b128 v[120:123], v103 offset:36864
	ds_read_b128 v[124:127], v104 offset:36864
	s_waitcnt vmcnt(0)
	ds_write_b128 v100, v[82:85] offset:0
	ds_write_b128 v165, v[86:89] offset:8192
	s_add_i32 s39, s38, 3
	s_cmp_lt_u32 s39, s96
	s_cbranch_scc0 .Lds0_sk1
	global_load_dwordx4 v[82:85], v[92:93], off offset:1024
	global_load_dwordx4 v[86:89], v[90:91], off offset:1280
	v_lshl_add_u64 v[92:93], v[92:93], 0, s[70:71]
	v_lshl_add_u64 v[90:91], v[90:91], 0, s[70:71]
.Lds0_sk1:
	v_add_f32_e32 v164, v142, v164
	v_add_f32_e32 v164, v143, v164
	s_waitcnt lgkmcnt(12)
	v_mfma_f32_32x32x16_bf16 v[18:33], v[168:171], v[152:155], v[18:33]
	v_cvt_pk_bf16_f32 v156, v144, v145
	v_cvt_pk_bf16_f32 v157, v146, v147
	v_cvt_pk_bf16_f32 v158, v148, v149
	v_cvt_pk_bf16_f32 v159, v150, v151
	v_add_f32_e32 v115, v144, v115
	v_add_f32_e32 v115, v145, v115
	s_waitcnt lgkmcnt(10)
	v_mfma_f32_32x32x16_bf16 v[2:17], v[172:175], v[152:155], v[2:17]
	v_add_f32_e32 v164, v146, v164
	v_add_f32_e32 v164, v147, v164
	v_add_f32_e32 v164, v148, v164
	v_add_f32_e32 v164, v149, v164
	v_add_f32_e32 v164, v150, v164
	v_add_f32_e32 v164, v151, v164
	s_waitcnt lgkmcnt(8)
	v_mfma_f32_32x32x16_bf16 v[18:33], v[176:179], v[156:159], v[18:33]
	v_exp_f32_e32 v50, v50
	v_exp_f32_e32 v51, v51
	v_exp_f32_e32 v52, v52
	v_exp_f32_e32 v53, v53
	s_waitcnt lgkmcnt(6)
	v_mfma_f32_32x32x16_bf16 v[2:17], v[180:183], v[156:159], v[2:17]
	ds_read_b64_tr_b16 v[168:169], v98 offset:28672
	ds_read_b64_tr_b16 v[170:171], v98 offset:28928
	ds_read_b64_tr_b16 v[172:173], v98 offset:29184
	ds_read_b64_tr_b16 v[174:175], v98 offset:29440
	ds_read_b64_tr_b16 v[176:177], v98 offset:30720
	ds_read_b64_tr_b16 v[178:179], v98 offset:30976
	ds_read_b64_tr_b16 v[180:181], v98 offset:31232
	ds_read_b64_tr_b16 v[182:183], v98 offset:31488
	v_exp_f32_e32 v54, v54
	v_exp_f32_e32 v55, v55
	v_exp_f32_e32 v56, v56
	v_exp_f32_e32 v57, v57
	s_waitcnt lgkmcnt(13)
	v_mfma_f32_32x32x16_bf16 v[136:151], v[106:109], v[66:69], 0
	v_cvt_pk_bf16_f32 v160, v50, v51
	v_cvt_pk_bf16_f32 v161, v52, v53
	v_cvt_pk_bf16_f32 v162, v54, v55
	v_cvt_pk_bf16_f32 v163, v56, v57
	v_add_f32_e32 v115, v50, v115
	v_add_f32_e32 v115, v51, v115
	s_waitcnt lgkmcnt(12)
	v_mfma_f32_32x32x16_bf16 v[136:151], v[110:113], v[70:73], v[136:151]
	v_exp_f32_e32 v58, v58
	v_exp_f32_e32 v59, v59
	v_exp_f32_e32 v60, v60
	v_exp_f32_e32 v61, v61
	v_add_f32_e32 v164, v52, v164
	v_add_f32_e32 v164, v53, v164
	s_waitcnt lgkmcnt(11)
	v_mfma_f32_32x32x16_bf16 v[136:151], v[120:123], v[74:77], v[136:151]
	v_exp_f32_e32 v62, v62
	v_exp_f32_e32 v63, v63
	v_exp_f32_e32 v64, v64
	v_exp_f32_e32 v65, v65
	v_add_f32_e32 v115, v54, v115
	v_add_f32_e32 v115, v55, v115
	s_waitcnt lgkmcnt(10)
	v_mfma_f32_32x32x16_bf16 v[136:151], v[124:127], v[78:81], v[136:151]
	v_cvt_pk_bf16_f32 v184, v58, v59
	v_cvt_pk_bf16_f32 v185, v60, v61
	v_cvt_pk_bf16_f32 v186, v62, v63
	v_cvt_pk_bf16_f32 v187, v64, v65
	v_add_f32_e32 v164, v56, v164
	v_add_f32_e32 v164, v57, v164
	s_waitcnt lgkmcnt(6)
	v_mfma_f32_32x32x16_bf16 v[18:33], v[168:171], v[160:163], v[18:33]
	v_add_f32_e32 v115, v58, v115
	v_add_f32_e32 v115, v59, v115
	v_add_f32_e32 v115, v60, v115
	v_add_f32_e32 v115, v61, v115
	s_waitcnt lgkmcnt(4)
	v_mfma_f32_32x32x16_bf16 v[2:17], v[172:175], v[160:163], v[2:17]
	v_add_f32_e32 v164, v62, v164
	v_add_f32_e32 v164, v63, v164
	v_add_f32_e32 v164, v64, v164
	v_add_f32_e32 v164, v65, v164
	s_waitcnt lgkmcnt(2)
	v_mfma_f32_32x32x16_bf16 v[18:33], v[176:179], v[184:187], v[18:33]
	s_waitcnt lgkmcnt(0)
	v_mfma_f32_32x32x16_bf16 v[2:17], v[180:183], v[184:187], v[2:17]
	s_waitcnt lgkmcnt(0)
	s_barrier
	s_add_i32 s38, s38, 1
	s_cmp_ge_u32 s38, s96
	s_cbranch_scc1 .Lds0_done
; template <int DV, int NK, int MODE, bool FIXM, int GRP>
; DI void attn_job(char* lds_wg, const AttnJob& J) {
;     ...
;       if (FIXM) {
;         const float nm = -J.m_init;
; #pragma unroll
;         for (int i = 0; i < 16; ++i) { sA[i] = __builtin_amdgcn_exp2f(fmaf(sA[i], C, nm)); sB[i] = __builtin_amdgcn_exp2f(fmaf(sB[i], C, nm)); l += sA[i] + sB[i]; }
;       } else {
;       float mx = sA[0];
; #pragma unroll
;       for (int i = 1; i < 16; ++i) mx = fmaxf(mx, sA[i]);
; #pragma unroll
;       for (int i = 0; i < 16; ++i) mx = fmaxf(mx, sB[i]);
;       mx = swapmax(mx);
;       const float mn = fmaxf(m, mx * C);
;       const float alpha = __builtin_amdgcn_exp2f(m - mn);
;       m = mn;
;       float ps = 0.f;
; #pragma unroll
;       for (int i = 0; i < 16; ++i) { sA[i] = __builtin_amdgcn_exp2f(fmaf(sA[i], C, -mn)); sB[i] = __builtin_amdgcn_exp2f(fmaf(sB[i], C, -mn)); ps += sA[i] + sB[i]; }
;       l = l * alpha + ps;
; #pragma unroll
;       for (int d = 0; d < NDV; ++d)
; #pragma unroll
;         for (int i = 0; i < 16; ++i) O[d][i] *= alpha;
;       }
;       bf16x8 pf[4];
;       { u32x4 w;
;         w.x = cvtpk(sA[0], sA[1]); w.y = cvtpk(sA[2], sA[3]); w.z = cvtpk(sA[4], sA[5]); w.w = cvtpk(sA[6], sA[7]); pf[0] = __builtin_bit_cast(bf16x8, w);
;         w.x = cvtpk(sA[8], sA[9]); w.y = cvtpk(sA[10], sA[11]); w.z = cvtpk(sA[12], sA[13]); w.w = cvtpk(sA[14], sA[15]); pf[1] = __builtin_bit_cast(bf16x8, w);
;         w.x = cvtpk(sB[0], sB[1]); w.y = cvtpk(sB[2], sB[3]); w.z = cvtpk(sB[4], sB[5]); w.w = cvtpk(sB[6], sB[7]); pf[2] = __builtin_bit_cast(bf16x8, w);
;         w.x = cvtpk(sB[8], sB[9]); w.y = cvtpk(sB[10], sB[11]); w.z = cvtpk(sB[12], sB[13]); w.w = cvtpk(sB[14], sB[15]); pf[3] = __builtin_bit_cast(bf16x8, w); }
;       const char* Vl = lds + stage * 32768 + NK * 8192 + vrd;
;       if (FIXM) {
;         bf16x8 vf[4][NDV];
; #pragma unroll
;         for (int ks = 0; ks < 4; ++ks) {
; #pragma unroll
;           for (int d = 0; d < NDV; ++d) {
;             const s16x4 lo = __builtin_amdgcn_ds_read_tr16_b64_v4i16((LAS s16x4*)(Vl + ks * 2 * NDV * 512 + d * 512));
;             const s16x4 hi = __builtin_amdgcn_ds_read_tr16_b64_v4i16((LAS s16x4*)(Vl + ks * 2 * NDV * 512 + d * 512 + 256));
;             vf[ks][d] = __builtin_shufflevector(lo, hi, 0, 1, 2, 3, 4, 5, 6, 7);
;           }
;         }
; #pragma unroll
	ds_read_b128 v[106:109], v0 offset:0
	ds_read_b128 v[110:113], v102 offset:0
	ds_read_b128 v[120:123], v103 offset:0
	ds_read_b128 v[124:127], v104 offset:0
	ds_read_b64_tr_b16 v[168:169], v98 offset:40960
	ds_read_b64_tr_b16 v[170:171], v98 offset:41216
	ds_read_b64_tr_b16 v[172:173], v98 offset:41472
	ds_read_b64_tr_b16 v[174:175], v98 offset:41728
	ds_read_b64_tr_b16 v[176:177], v98 offset:43008
	ds_read_b64_tr_b16 v[178:179], v98 offset:43264
	ds_read_b64_tr_b16 v[180:181], v98 offset:43520
	ds_read_b64_tr_b16 v[182:183], v98 offset:43776
	v_exp_f32_e32 v34, v34
	v_exp_f32_e32 v35, v35
	v_exp_f32_e32 v36, v36
	v_exp_f32_e32 v37, v37
	v_exp_f32_e32 v38, v38
	v_exp_f32_e32 v39, v39
	v_exp_f32_e32 v40, v40
	v_exp_f32_e32 v41, v41
	s_waitcnt lgkmcnt(11)
	v_mfma_f32_32x32x16_bf16 v[50:65], v[106:109], v[66:69], 0
	v_cvt_pk_bf16_f32 v152, v34, v35
	v_cvt_pk_bf16_f32 v153, v36, v37
	v_cvt_pk_bf16_f32 v154, v38, v39
	v_cvt_pk_bf16_f32 v155, v40, v41
	v_add_f32_e32 v115, v34, v115
	v_add_f32_e32 v115, v35, v115
	s_waitcnt lgkmcnt(10)
	v_mfma_f32_32x32x16_bf16 v[50:65], v[110:113], v[70:73], v[50:65]
	v_exp_f32_e32 v42, v42
	v_exp_f32_e32 v43, v43
	v_exp_f32_e32 v44, v44
	v_exp_f32_e32 v45, v45
	v_add_f32_e32 v164, v36, v164
	v_add_f32_e32 v164, v37, v164
	s_waitcnt lgkmcnt(9)
	v_mfma_f32_32x32x16_bf16 v[50:65], v[120:123], v[74:77], v[50:65]
	v_exp_f32_e32 v46, v46
	v_exp_f32_e32 v47, v47
	v_exp_f32_e32 v48, v48
	v_exp_f32_e32 v49, v49
	v_add_f32_e32 v115, v38, v115
	v_add_f32_e32 v115, v39, v115
	s_waitcnt lgkmcnt(8)
	v_mfma_f32_32x32x16_bf16 v[50:65], v[124:127], v[78:81], v[50:65]
	ds_read_b128 v[106:109], v0 offset:4096
	ds_read_b128 v[110:113], v102 offset:4096
	ds_read_b128 v[120:123], v103 offset:4096
	ds_read_b128 v[124:127], v104 offset:4096
	s_waitcnt vmcnt(0)
	ds_write_b128 v100, v[82:85] offset:16384
	ds_write_b128 v165, v[86:89] offset:24576
	s_add_i32 s39, s38, 3
	s_cmp_lt_u32 s39, s96
	s_cbranch_scc0 .Lds0_sk2
	global_load_dwordx4 v[82:85], v[92:93], off offset:1024
	global_load_dwordx4 v[86:89], v[90:91], off offset:1280
	v_lshl_add_u64 v[92:93], v[92:93], 0, s[70:71]
	v_lshl_add_u64 v[90:91], v[90:91], 0, s[70:71]
.Lds0_sk2:
	v_add_f32_e32 v164, v40, v164
	v_add_f32_e32 v164, v41, v164
	s_waitcnt lgkmcnt(12)
	v_mfma_f32_32x32x16_bf16 v[18:33], v[168:171], v[152:155], v[18:33]
	v_cvt_pk_bf16_f32 v156, v42, v43
	v_cvt_pk_bf16_f32 v157, v44, v45
	v_cvt_pk_bf16_f32 v158, v46, v47
	v_cvt_pk_bf16_f32 v159, v48, v49
	v_add_f32_e32 v115, v42, v115
	v_add_f32_e32 v115, v43, v115
	s_waitcnt lgkmcnt(10)
	v_mfma_f32_32x32x16_bf16 v[2:17], v[172:175], v[152:155], v[2:17]
	v_add_f32_e32 v164, v44, v164
	v_add_f32_e32 v164, v45, v164
	v_add_f32_e32 v164, v46, v164
	v_add_f32_e32 v164, v47, v164
	v_add_f32_e32 v164, v48, v164
	v_add_f32_e32 v164, v49, v164
	s_waitcnt lgkmcnt(8)
	v_mfma_f32_32x32x16_bf16 v[18:33], v[176:179], v[156:159], v[18:33]
	v_exp_f32_e32 v136, v136
	v_exp_f32_e32 v137, v137
	v_exp_f32_e32 v138, v138
	v_exp_f32_e32 v139, v139
	s_waitcnt lgkmcnt(6)
	v_mfma_f32_32x32x16_bf16 v[2:17], v[180:183], v[156:159], v[2:17]
	ds_read_b64_tr_b16 v[168:169], v98 offset:45056
	ds_read_b64_tr_b16 v[170:171], v98 offset:45312
	ds_read_b64_tr_b16 v[172:173], v98 offset:45568
	ds_read_b64_tr_b16 v[174:175], v98 offset:45824
	ds_read_b64_tr_b16 v[176:177], v98 offset:47104
	ds_read_b64_tr_b16 v[178:179], v98 offset:47360
	ds_read_b64_tr_b16 v[180:181], v98 offset:47616
	ds_read_b64_tr_b16 v[182:183], v98 offset:47872
	v_exp_f32_e32 v140, v140
	v_exp_f32_e32 v141, v141
	v_exp_f32_e32 v142, v142
	v_exp_f32_e32 v143, v143
	s_waitcnt lgkmcnt(13)
	v_mfma_f32_32x32x16_bf16 v[34:49], v[106:109], v[66:69], 0
	v_cvt_pk_bf16_f32 v160, v136, v137
	v_cvt_pk_bf16_f32 v161, v138, v139
	v_cvt_pk_bf16_f32 v162, v140, v141
	v_cvt_pk_bf16_f32 v163, v142, v143
	v_add_f32_e32 v115, v136, v115
	v_add_f32_e32 v115, v137, v115
	s_waitcnt lgkmcnt(12)
	v_mfma_f32_32x32x16_bf16 v[34:49], v[110:113], v[70:73], v[34:49]
	v_exp_f32_e32 v144, v144
	v_exp_f32_e32 v145, v145
	v_exp_f32_e32 v146, v146
	v_exp_f32_e32 v147, v147
	v_add_f32_e32 v164, v138, v164
	v_add_f32_e32 v164, v139, v164
	s_waitcnt lgkmcnt(11)
	v_mfma_f32_32x32x16_bf16 v[34:49], v[120:123], v[74:77], v[34:49]
	v_exp_f32_e32 v148, v148
	v_exp_f32_e32 v149, v149
	v_exp_f32_e32 v150, v150
	v_exp_f32_e32 v151, v151
	v_add_f32_e32 v115, v140, v115
	v_add_f32_e32 v115, v141, v115
	s_waitcnt lgkmcnt(10)
	v_mfma_f32_32x32x16_bf16 v[34:49], v[124:127], v[78:81], v[34:49]
	v_cvt_pk_bf16_f32 v184, v144, v145
	v_cvt_pk_bf16_f32 v185, v146, v147
	v_cvt_pk_bf16_f32 v186, v148, v149
	v_cvt_pk_bf16_f32 v187, v150, v151
	v_add_f32_e32 v164, v142, v164
	v_add_f32_e32 v164, v143, v164
	s_waitcnt lgkmcnt(6)
	v_mfma_f32_32x32x16_bf16 v[18:33], v[168:171], v[160:163], v[18:33]
	v_add_f32_e32 v115, v144, v115
	v_add_f32_e32 v115, v145, v115
	v_add_f32_e32 v115, v146, v115
	v_add_f32_e32 v115, v147, v115
	s_waitcnt lgkmcnt(4)
	v_mfma_f32_32x32x16_bf16 v[2:17], v[172:175], v[160:163], v[2:17]
	v_add_f32_e32 v164, v148, v164
	v_add_f32_e32 v164, v149, v164
	v_add_f32_e32 v164, v150, v164
	v_add_f32_e32 v164, v151, v164
	s_waitcnt lgkmcnt(2)
	v_mfma_f32_32x32x16_bf16 v[18:33], v[176:179], v[184:187], v[18:33]
	s_waitcnt lgkmcnt(0)
	v_mfma_f32_32x32x16_bf16 v[2:17], v[180:183], v[184:187], v[2:17]
	s_waitcnt lgkmcnt(0)
	s_barrier
	s_add_i32 s38, s38, 1
	s_cmp_ge_u32 s38, s96
	s_cbranch_scc1 .Lds0_done
	s_branch .Lds0_loop

; template <int DV, int NK, int MODE, bool FIXM, int GRP>
; DI void attn_job(char* lds_wg, const AttnJob& J) {
;     ...
;       if (FIXM) {
;         const float nm = -J.m_init;
; #pragma unroll
;         for (int i = 0; i < 16; ++i) { sA[i] = __builtin_amdgcn_exp2f(fmaf(sA[i], C, nm)); sB[i] = __builtin_amdgcn_exp2f(fmaf(sB[i], C, nm)); l += sA[i] + sB[i]; }
;       } else {
;       float mx = sA[0];
; #pragma unroll
;       for (int i = 1; i < 16; ++i) mx = fmaxf(mx, sA[i]);
; #pragma unroll
;       for (int i = 0; i < 16; ++i) mx = fmaxf(mx, sB[i]);
;       mx = swapmax(mx);
;       const float mn = fmaxf(m, mx * C);
;       const float alpha = __builtin_amdgcn_exp2f(m - mn);
;       m = mn;
;       float ps = 0.f;
; #pragma unroll
;       for (int i = 0; i < 16; ++i) { sA[i] = __builtin_amdgcn_exp2f(fmaf(sA[i], C, -mn)); sB[i] = __builtin_amdgcn_exp2f(fmaf(sB[i], C, -mn)); ps += sA[i] + sB[i]; }
;       l = l * alpha + ps;
; #pragma unroll
;       for (int d = 0; d < NDV; ++d)
; #pragma unroll
;         for (int i = 0; i < 16; ++i) O[d][i] *= alpha;
;       }
;       bf16x8 pf[4];
;       { u32x4 w;
;         w.x = cvtpk(sA[0], sA[1]); w.y = cvtpk(sA[2], sA[3]); w.z = cvtpk(sA[4], sA[5]); w.w = cvtpk(sA[6], sA[7]); pf[0] = __builtin_bit_cast(bf16x8, w);
;         w.x = cvtpk(sA[8], sA[9]); w.y = cvtpk(sA[10], sA[11]); w.z = cvtpk(sA[12], sA[13]); w.w = cvtpk(sA[14], sA[15]); pf[1] = __builtin_bit_cast(bf16x8, w);
;         w.x = cvtpk(sB[0], sB[1]); w.y = cvtpk(sB[2], sB[3]); w.z = cvtpk(sB[4], sB[5]); w.w = cvtpk(sB[6], sB[7]); pf[2] = __builtin_bit_cast(bf16x8, w);
;         w.x = cvtpk(sB[8], sB[9]); w.y = cvtpk(sB[10], sB[11]); w.z = cvtpk(sB[12], sB[13]); w.w = cvtpk(sB[14], sB[15]); pf[3] = __builtin_bit_cast(bf16x8, w); }
;       const char* Vl = lds + stage * 32768 + NK * 8192 + vrd;
;       if (FIXM) {
;         bf16x8 vf[4][NDV];
; #pragma unroll
;         for (int ks = 0; ks < 4; ++ks) {
; #pragma unroll
;           for (int d = 0; d < NDV; ++d) {
;             const s16x4 lo = __builtin_amdgcn_ds_read_tr16_b64_v4i16((LAS s16x4*)(Vl + ks * 2 * NDV * 512 + d * 512));
;             const s16x4 hi = __builtin_amdgcn_ds_read_tr16_b64_v4i16((LAS s16x4*)(Vl + ks * 2 * NDV * 512 + d * 512 + 256));
;             vf[ks][d] = __builtin_shufflevector(lo, hi, 0, 1, 2, 3, 4, 5, 6, 7);
;           }
;         }
; #pragma unroll
.Lds1_loop:
	ds_read_b128 v[106:109], v0 offset:16384
	ds_read_b128 v[110:113], v102 offset:16384
	ds_read_b128 v[120:123], v103 offset:16384
	ds_read_b128 v[124:127], v104 offset:16384
	ds_read_b64_tr_b16 v[168:169], v98 offset:8192
	ds_read_b64_tr_b16 v[170:171], v98 offset:8448
	ds_read_b64_tr_b16 v[172:173], v98 offset:8704
	ds_read_b64_tr_b16 v[174:175], v98 offset:8960
	ds_read_b64_tr_b16 v[176:177], v98 offset:10240
	ds_read_b64_tr_b16 v[178:179], v98 offset:10496
	ds_read_b64_tr_b16 v[180:181], v98 offset:10752
	ds_read_b64_tr_b16 v[182:183], v98 offset:11008
	v_exp_f32_e32 v50, v50
	v_exp_f32_e32 v51, v51
	v_exp_f32_e32 v52, v52
	v_exp_f32_e32 v53, v53
	v_exp_f32_e32 v54, v54
	v_exp_f32_e32 v55, v55
	v_exp_f32_e32 v56, v56
	v_exp_f32_e32 v57, v57
	s_waitcnt lgkmcnt(11)
	v_mfma_f32_32x32x16_bf16 v[136:151], v[106:109], v[66:69], 0
	v_cvt_pk_bf16_f32 v152, v50, v51
	v_cvt_pk_bf16_f32 v153, v52, v53
	v_cvt_pk_bf16_f32 v154, v54, v55
	v_cvt_pk_bf16_f32 v155, v56, v57
	v_add_f32_e32 v115, v50, v115
	v_add_f32_e32 v115, v51, v115
	s_waitcnt lgkmcnt(10)
	v_mfma_f32_32x32x16_bf16 v[136:151], v[110:113], v[70:73], v[136:151]
	v_exp_f32_e32 v58, v58
	v_exp_f32_e32 v59, v59
	v_exp_f32_e32 v60, v60
	v_exp_f32_e32 v61, v61
	v_add_f32_e32 v164, v52, v164
	v_add_f32_e32 v164, v53, v164
	s_waitcnt lgkmcnt(9)
	v_mfma_f32_32x32x16_bf16 v[136:151], v[120:123], v[74:77], v[136:151]
	v_exp_f32_e32 v62, v62
	v_exp_f32_e32 v63, v63
	v_exp_f32_e32 v64, v64
	v_exp_f32_e32 v65, v65
	v_add_f32_e32 v115, v54, v115
	v_add_f32_e32 v115, v55, v115
	s_waitcnt lgkmcnt(8)
	v_mfma_f32_32x32x16_bf16 v[136:151], v[124:127], v[78:81], v[136:151]
	ds_read_b128 v[106:109], v0 offset:20480
	ds_read_b128 v[110:113], v102 offset:20480
	ds_read_b128 v[120:123], v103 offset:20480
	ds_read_b128 v[124:127], v104 offset:20480
	s_waitcnt vmcnt(0)
	ds_write_b128 v100, v[82:85] offset:32768
	ds_write_b128 v165, v[86:89] offset:40960
	s_add_i32 s31, s30, 3
	s_cmp_lt_u32 s31, s96
	s_cbranch_scc0 .Lds1_sk0
	global_load_dwordx4 v[82:85], v[92:93], off offset:1024
	global_load_dwordx4 v[86:89], v[90:91], off offset:1280
	v_lshl_add_u64 v[92:93], v[92:93], 0, s[10:11]
	v_lshl_add_u64 v[90:91], v[90:91], 0, s[10:11]
.Lds1_sk0:
	v_add_f32_e32 v164, v56, v164
	v_add_f32_e32 v164, v57, v164
	s_waitcnt lgkmcnt(12)
	v_mfma_f32_32x32x16_bf16 v[18:33], v[168:171], v[152:155], v[18:33]
	v_cvt_pk_bf16_f32 v156, v58, v59
	v_cvt_pk_bf16_f32 v157, v60, v61
	v_cvt_pk_bf16_f32 v158, v62, v63
	v_cvt_pk_bf16_f32 v159, v64, v65
	v_add_f32_e32 v115, v58, v115
	v_add_f32_e32 v115, v59, v115
	s_waitcnt lgkmcnt(10)
	v_mfma_f32_32x32x16_bf16 v[2:17], v[172:175], v[152:155], v[2:17]
	v_add_f32_e32 v164, v60, v164
	v_add_f32_e32 v164, v61, v164
	v_add_f32_e32 v164, v62, v164
	v_add_f32_e32 v164, v63, v164
	v_add_f32_e32 v164, v64, v164
	v_add_f32_e32 v164, v65, v164
	s_waitcnt lgkmcnt(8)
	v_mfma_f32_32x32x16_bf16 v[18:33], v[176:179], v[156:159], v[18:33]
	v_exp_f32_e32 v34, v34
	v_exp_f32_e32 v35, v35
	v_exp_f32_e32 v36, v36
	v_exp_f32_e32 v37, v37
	s_waitcnt lgkmcnt(6)
	v_mfma_f32_32x32x16_bf16 v[2:17], v[180:183], v[156:159], v[2:17]
	ds_read_b64_tr_b16 v[168:169], v98 offset:12288
	ds_read_b64_tr_b16 v[170:171], v98 offset:12544
	ds_read_b64_tr_b16 v[172:173], v98 offset:12800
	ds_read_b64_tr_b16 v[174:175], v98 offset:13056
	ds_read_b64_tr_b16 v[176:177], v98 offset:14336
	ds_read_b64_tr_b16 v[178:179], v98 offset:14592
	ds_read_b64_tr_b16 v[180:181], v98 offset:14848
	ds_read_b64_tr_b16 v[182:183], v98 offset:15104
	v_exp_f32_e32 v38, v38
	v_exp_f32_e32 v39, v39
	v_exp_f32_e32 v40, v40
	v_exp_f32_e32 v41, v41
	s_waitcnt lgkmcnt(13)
	v_mfma_f32_32x32x16_bf16 v[50:65], v[106:109], v[66:69], 0
	v_cvt_pk_bf16_f32 v160, v34, v35
	v_cvt_pk_bf16_f32 v161, v36, v37
	v_cvt_pk_bf16_f32 v162, v38, v39
	v_cvt_pk_bf16_f32 v163, v40, v41
	v_add_f32_e32 v115, v34, v115
	v_add_f32_e32 v115, v35, v115
	s_waitcnt lgkmcnt(12)
	v_mfma_f32_32x32x16_bf16 v[50:65], v[110:113], v[70:73], v[50:65]
	v_exp_f32_e32 v42, v42
	v_exp_f32_e32 v43, v43
	v_exp_f32_e32 v44, v44
	v_exp_f32_e32 v45, v45
	v_add_f32_e32 v164, v36, v164
	v_add_f32_e32 v164, v37, v164
	s_waitcnt lgkmcnt(11)
	v_mfma_f32_32x32x16_bf16 v[50:65], v[120:123], v[74:77], v[50:65]
	v_exp_f32_e32 v46, v46
	v_exp_f32_e32 v47, v47
	v_exp_f32_e32 v48, v48
	v_exp_f32_e32 v49, v49
	v_add_f32_e32 v115, v38, v115
	v_add_f32_e32 v115, v39, v115
	s_waitcnt lgkmcnt(10)
	v_mfma_f32_32x32x16_bf16 v[50:65], v[124:127], v[78:81], v[50:65]
	v_cvt_pk_bf16_f32 v184, v42, v43
	v_cvt_pk_bf16_f32 v185, v44, v45
	v_cvt_pk_bf16_f32 v186, v46, v47
	v_cvt_pk_bf16_f32 v187, v48, v49
	v_add_f32_e32 v164, v40, v164
	v_add_f32_e32 v164, v41, v164
	s_waitcnt lgkmcnt(6)
	v_mfma_f32_32x32x16_bf16 v[18:33], v[168:171], v[160:163], v[18:33]
	v_add_f32_e32 v115, v42, v115
	v_add_f32_e32 v115, v43, v115
	v_add_f32_e32 v115, v44, v115
	v_add_f32_e32 v115, v45, v115
	s_waitcnt lgkmcnt(4)
	v_mfma_f32_32x32x16_bf16 v[2:17], v[172:175], v[160:163], v[2:17]
	v_add_f32_e32 v164, v46, v164
	v_add_f32_e32 v164, v47, v164
	v_add_f32_e32 v164, v48, v164
	v_add_f32_e32 v164, v49, v164
	s_waitcnt lgkmcnt(2)
	v_mfma_f32_32x32x16_bf16 v[18:33], v[176:179], v[184:187], v[18:33]
	s_waitcnt lgkmcnt(0)
	v_mfma_f32_32x32x16_bf16 v[2:17], v[180:183], v[184:187], v[2:17]
	s_waitcnt lgkmcnt(0)
	s_barrier
	s_add_i32 s30, s30, 1
	s_cmp_ge_u32 s30, s96
	s_cbranch_scc1 .Lds1_done
; template <int DV, int NK, int MODE, bool FIXM, int GRP>
; DI void attn_job(char* lds_wg, const AttnJob& J) {
;     ...
;       if (FIXM) {
;         const float nm = -J.m_init;
; #pragma unroll
;         for (int i = 0; i < 16; ++i) { sA[i] = __builtin_amdgcn_exp2f(fmaf(sA[i], C, nm)); sB[i] = __builtin_amdgcn_exp2f(fmaf(sB[i], C, nm)); l += sA[i] + sB[i]; }
;       } else {
;       float mx = sA[0];
; #pragma unroll
;       for (int i = 1; i < 16; ++i) mx = fmaxf(mx, sA[i]);
; #pragma unroll
;       for (int i = 0; i < 16; ++i) mx = fmaxf(mx, sB[i]);
;       mx = swapmax(mx);
;       const float mn = fmaxf(m, mx * C);
;       const float alpha = __builtin_amdgcn_exp2f(m - mn);
;       m = mn;
;       float ps = 0.f;
; #pragma unroll
;       for (int i = 0; i < 16; ++i) { sA[i] = __builtin_amdgcn_exp2f(fmaf(sA[i], C, -mn)); sB[i] = __builtin_amdgcn_exp2f(fmaf(sB[i], C, -mn)); ps += sA[i] + sB[i]; }
;       l = l * alpha + ps;
; #pragma unroll
;       for (int d = 0; d < NDV; ++d)
; #pragma unroll
;         for (int i = 0; i < 16; ++i) O[d][i] *= alpha;
;       }
;       bf16x8 pf[4];
;       { u32x4 w;
;         w.x = cvtpk(sA[0], sA[1]); w.y = cvtpk(sA[2], sA[3]); w.z = cvtpk(sA[4], sA[5]); w.w = cvtpk(sA[6], sA[7]); pf[0] = __builtin_bit_cast(bf16x8, w);
;         w.x = cvtpk(sA[8], sA[9]); w.y = cvtpk(sA[10], sA[11]); w.z = cvtpk(sA[12], sA[13]); w.w = cvtpk(sA[14], sA[15]); pf[1] = __builtin_bit_cast(bf16x8, w);
;         w.x = cvtpk(sB[0], sB[1]); w.y = cvtpk(sB[2], sB[3]); w.z = cvtpk(sB[4], sB[5]); w.w = cvtpk(sB[6], sB[7]); pf[2] = __builtin_bit_cast(bf16x8, w);
;         w.x = cvtpk(sB[8], sB[9]); w.y = cvtpk(sB[10], sB[11]); w.z = cvtpk(sB[12], sB[13]); w.w = cvtpk(sB[14], sB[15]); pf[3] = __builtin_bit_cast(bf16x8, w); }
;       const char* Vl = lds + stage * 32768 + NK * 8192 + vrd;
;       if (FIXM) {
;         bf16x8 vf[4][NDV];
; #pragma unroll
;         for (int ks = 0; ks < 4; ++ks) {
; #pragma unroll
;           for (int d = 0; d < NDV; ++d) {
;             const s16x4 lo = __builtin_amdgcn_ds_read_tr16_b64_v4i16((LAS s16x4*)(Vl + ks * 2 * NDV * 512 + d * 512));
;             const s16x4 hi = __builtin_amdgcn_ds_read_tr16_b64_v4i16((LAS s16x4*)(Vl + ks * 2 * NDV * 512 + d * 512 + 256));
;             vf[ks][d] = __builtin_shufflevector(lo, hi, 0, 1, 2, 3, 4, 5, 6, 7);
;           }
;         }
; #pragma unroll
	ds_read_b128 v[106:109], v0 offset:32768
	ds_read_b128 v[110:113], v102 offset:32768
	ds_read_b128 v[120:123], v103 offset:32768
	ds_read_b128 v[124:127], v104 offset:32768
	ds_read_b64_tr_b16 v[168:169], v98 offset:24576
	ds_read_b64_tr_b16 v[170:171], v98 offset:24832
	ds_read_b64_tr_b16 v[172:173], v98 offset:25088
	ds_read_b64_tr_b16 v[174:175], v98 offset:25344
	ds_read_b64_tr_b16 v[176:177], v98 offset:26624
	ds_read_b64_tr_b16 v[178:179], v98 offset:26880
	ds_read_b64_tr_b16 v[180:181], v98 offset:27136
	ds_read_b64_tr_b16 v[182:183], v98 offset:27392
	v_exp_f32_e32 v136, v136
	v_exp_f32_e32 v137, v137
	v_exp_f32_e32 v138, v138
	v_exp_f32_e32 v139, v139
	v_exp_f32_e32 v140, v140
	v_exp_f32_e32 v141, v141
	v_exp_f32_e32 v142, v142
	v_exp_f32_e32 v143, v143
	s_waitcnt lgkmcnt(11)
	v_mfma_f32_32x32x16_bf16 v[34:49], v[106:109], v[66:69], 0
	v_cvt_pk_bf16_f32 v152, v136, v137
	v_cvt_pk_bf16_f32 v153, v138, v139
	v_cvt_pk_bf16_f32 v154, v140, v141
	v_cvt_pk_bf16_f32 v155, v142, v143
	v_add_f32_e32 v115, v136, v115
	v_add_f32_e32 v115, v137, v115
	s_waitcnt lgkmcnt(10)
	v_mfma_f32_32x32x16_bf16 v[34:49], v[110:113], v[70:73], v[34:49]
	v_exp_f32_e32 v144, v144
	v_exp_f32_e32 v145, v145
	v_exp_f32_e32 v146, v146
	v_exp_f32_e32 v147, v147
	v_add_f32_e32 v164, v138, v164
	v_add_f32_e32 v164, v139, v164
	s_waitcnt lgkmcnt(9)
	v_mfma_f32_32x32x16_bf16 v[34:49], v[120:123], v[74:77], v[34:49]
	v_exp_f32_e32 v148, v148
	v_exp_f32_e32 v149, v149
	v_exp_f32_e32 v150, v150
	v_exp_f32_e32 v151, v151
	v_add_f32_e32 v115, v140, v115
	v_add_f32_e32 v115, v141, v115
	s_waitcnt lgkmcnt(8)
	v_mfma_f32_32x32x16_bf16 v[34:49], v[124:127], v[78:81], v[34:49]
	ds_read_b128 v[106:109], v0 offset:36864
	ds_read_b128 v[110:113], v102 offset:36864
	ds_read_b128 v[120:123], v103 offset:36864
	ds_read_b128 v[124:127], v104 offset:36864
	s_waitcnt vmcnt(0)
	ds_write_b128 v100, v[82:85] offset:0
	ds_write_b128 v165, v[86:89] offset:8192
	s_add_i32 s31, s30, 3
	s_cmp_lt_u32 s31, s96
	s_cbranch_scc0 .Lds1_sk1
	global_load_dwordx4 v[82:85], v[92:93], off offset:1024
	global_load_dwordx4 v[86:89], v[90:91], off offset:1280
	v_lshl_add_u64 v[92:93], v[92:93], 0, s[10:11]
	v_lshl_add_u64 v[90:91], v[90:91], 0, s[10:11]
.Lds1_sk1:
	v_add_f32_e32 v164, v142, v164
	v_add_f32_e32 v164, v143, v164
	s_waitcnt lgkmcnt(12)
	v_mfma_f32_32x32x16_bf16 v[18:33], v[168:171], v[152:155], v[18:33]
	v_cvt_pk_bf16_f32 v156, v144, v145
	v_cvt_pk_bf16_f32 v157, v146, v147
	v_cvt_pk_bf16_f32 v158, v148, v149
	v_cvt_pk_bf16_f32 v159, v150, v151
	v_add_f32_e32 v115, v144, v115
	v_add_f32_e32 v115, v145, v115
	s_waitcnt lgkmcnt(10)
	v_mfma_f32_32x32x16_bf16 v[2:17], v[172:175], v[152:155], v[2:17]
	v_add_f32_e32 v164, v146, v164
	v_add_f32_e32 v164, v147, v164
	v_add_f32_e32 v164, v148, v164
	v_add_f32_e32 v164, v149, v164
	v_add_f32_e32 v164, v150, v164
	v_add_f32_e32 v164, v151, v164
	s_waitcnt lgkmcnt(8)
	v_mfma_f32_32x32x16_bf16 v[18:33], v[176:179], v[156:159], v[18:33]
	v_exp_f32_e32 v50, v50
	v_exp_f32_e32 v51, v51
	v_exp_f32_e32 v52, v52
	v_exp_f32_e32 v53, v53
	s_waitcnt lgkmcnt(6)
	v_mfma_f32_32x32x16_bf16 v[2:17], v[180:183], v[156:159], v[2:17]
	ds_read_b64_tr_b16 v[168:169], v98 offset:28672
	ds_read_b64_tr_b16 v[170:171], v98 offset:28928
	ds_read_b64_tr_b16 v[172:173], v98 offset:29184
	ds_read_b64_tr_b16 v[174:175], v98 offset:29440
	ds_read_b64_tr_b16 v[176:177], v98 offset:30720
	ds_read_b64_tr_b16 v[178:179], v98 offset:30976
	ds_read_b64_tr_b16 v[180:181], v98 offset:31232
	ds_read_b64_tr_b16 v[182:183], v98 offset:31488
	v_exp_f32_e32 v54, v54
	v_exp_f32_e32 v55, v55
	v_exp_f32_e32 v56, v56
	v_exp_f32_e32 v57, v57
	s_waitcnt lgkmcnt(13)
	v_mfma_f32_32x32x16_bf16 v[136:151], v[106:109], v[66:69], 0
	v_cvt_pk_bf16_f32 v160, v50, v51
	v_cvt_pk_bf16_f32 v161, v52, v53
	v_cvt_pk_bf16_f32 v162, v54, v55
	v_cvt_pk_bf16_f32 v163, v56, v57
	v_add_f32_e32 v115, v50, v115
	v_add_f32_e32 v115, v51, v115
	s_waitcnt lgkmcnt(12)
	v_mfma_f32_32x32x16_bf16 v[136:151], v[110:113], v[70:73], v[136:151]
	v_exp_f32_e32 v58, v58
	v_exp_f32_e32 v59, v59
	v_exp_f32_e32 v60, v60
	v_exp_f32_e32 v61, v61
	v_add_f32_e32 v164, v52, v164
	v_add_f32_e32 v164, v53, v164
	s_waitcnt lgkmcnt(11)
	v_mfma_f32_32x32x16_bf16 v[136:151], v[120:123], v[74:77], v[136:151]
	v_exp_f32_e32 v62, v62
	v_exp_f32_e32 v63, v63
	v_exp_f32_e32 v64, v64
	v_exp_f32_e32 v65, v65
	v_add_f32_e32 v115, v54, v115
	v_add_f32_e32 v115, v55, v115
	s_waitcnt lgkmcnt(10)
	v_mfma_f32_32x32x16_bf16 v[136:151], v[124:127], v[78:81], v[136:151]
	v_cvt_pk_bf16_f32 v184, v58, v59
	v_cvt_pk_bf16_f32 v185, v60, v61
	v_cvt_pk_bf16_f32 v186, v62, v63
	v_cvt_pk_bf16_f32 v187, v64, v65
	v_add_f32_e32 v164, v56, v164
	v_add_f32_e32 v164, v57, v164
	s_waitcnt lgkmcnt(6)
	v_mfma_f32_32x32x16_bf16 v[18:33], v[168:171], v[160:163], v[18:33]
	v_add_f32_e32 v115, v58, v115
	v_add_f32_e32 v115, v59, v115
	v_add_f32_e32 v115, v60, v115
	v_add_f32_e32 v115, v61, v115
	s_waitcnt lgkmcnt(4)
	v_mfma_f32_32x32x16_bf16 v[2:17], v[172:175], v[160:163], v[2:17]
	v_add_f32_e32 v164, v62, v164
	v_add_f32_e32 v164, v63, v164
	v_add_f32_e32 v164, v64, v164
	v_add_f32_e32 v164, v65, v164
	s_waitcnt lgkmcnt(2)
	v_mfma_f32_32x32x16_bf16 v[18:33], v[176:179], v[184:187], v[18:33]
	s_waitcnt lgkmcnt(0)
	v_mfma_f32_32x32x16_bf16 v[2:17], v[180:183], v[184:187], v[2:17]
	s_waitcnt lgkmcnt(0)
	s_barrier
	s_add_i32 s30, s30, 1
	s_cmp_ge_u32 s30, s96
	s_cbranch_scc1 .Lds1_done
; template <int DV, int NK, int MODE, bool FIXM, int GRP>
; DI void attn_job(char* lds_wg, const AttnJob& J) {
;     ...
;       if (FIXM) {
;         const float nm = -J.m_init;
; #pragma unroll
;         for (int i = 0; i < 16; ++i) { sA[i] = __builtin_amdgcn_exp2f(fmaf(sA[i], C, nm)); sB[i] = __builtin_amdgcn_exp2f(fmaf(sB[i], C, nm)); l += sA[i] + sB[i]; }
;       } else {
;       float mx = sA[0];
; #pragma unroll
;       for (int i = 1; i < 16; ++i) mx = fmaxf(mx, sA[i]);
; #pragma unroll
;       for (int i = 0; i < 16; ++i) mx = fmaxf(mx, sB[i]);
;       mx = swapmax(mx);
;       const float mn = fmaxf(m, mx * C);
;       const float alpha = __builtin_amdgcn_exp2f(m - mn);
;       m = mn;
;       float ps = 0.f;
; #pragma unroll
;       for (int i = 0; i < 16; ++i) { sA[i] = __builtin_amdgcn_exp2f(fmaf(sA[i], C, -mn)); sB[i] = __builtin_amdgcn_exp2f(fmaf(sB[i], C, -mn)); ps += sA[i] + sB[i]; }
;       l = l * alpha + ps;
; #pragma unroll
;       for (int d = 0; d < NDV; ++d)
; #pragma unroll
;         for (int i = 0; i < 16; ++i) O[d][i] *= alpha;
;       }
;       bf16x8 pf[4];
;       { u32x4 w;
;         w.x = cvtpk(sA[0], sA[1]); w.y = cvtpk(sA[2], sA[3]); w.z = cvtpk(sA[4], sA[5]); w.w = cvtpk(sA[6], sA[7]); pf[0] = __builtin_bit_cast(bf16x8, w);
;         w.x = cvtpk(sA[8], sA[9]); w.y = cvtpk(sA[10], sA[11]); w.z = cvtpk(sA[12], sA[13]); w.w = cvtpk(sA[14], sA[15]); pf[1] = __builtin_bit_cast(bf16x8, w);
;         w.x = cvtpk(sB[0], sB[1]); w.y = cvtpk(sB[2], sB[3]); w.z = cvtpk(sB[4], sB[5]); w.w = cvtpk(sB[6], sB[7]); pf[2] = __builtin_bit_cast(bf16x8, w);
;         w.x = cvtpk(sB[8], sB[9]); w.y = cvtpk(sB[10], sB[11]); w.z = cvtpk(sB[12], sB[13]); w.w = cvtpk(sB[14], sB[15]); pf[3] = __builtin_bit_cast(bf16x8, w); }
;       const char* Vl = lds + stage * 32768 + NK * 8192 + vrd;
;       if (FIXM) {
;         bf16x8 vf[4][NDV];
; #pragma unroll
;         for (int ks = 0; ks < 4; ++ks) {
; #pragma unroll
;           for (int d = 0; d < NDV; ++d) {
;             const s16x4 lo = __builtin_amdgcn_ds_read_tr16_b64_v4i16((LAS s16x4*)(Vl + ks * 2 * NDV * 512 + d * 512));
;             const s16x4 hi = __builtin_amdgcn_ds_read_tr16_b64_v4i16((LAS s16x4*)(Vl + ks * 2 * NDV * 512 + d * 512 + 256));
;             vf[ks][d] = __builtin_shufflevector(lo, hi, 0, 1, 2, 3, 4, 5, 6, 7);
;           }
;         }
; #pragma unroll
	ds_read_b128 v[106:109], v0 offset:0
	ds_read_b128 v[110:113], v102 offset:0
	ds_read_b128 v[120:123], v103 offset:0
	ds_read_b128 v[124:127], v104 offset:0
	ds_read_b64_tr_b16 v[168:169], v98 offset:40960
	ds_read_b64_tr_b16 v[170:171], v98 offset:41216
	ds_read_b64_tr_b16 v[172:173], v98 offset:41472
	ds_read_b64_tr_b16 v[174:175], v98 offset:41728
	ds_read_b64_tr_b16 v[176:177], v98 offset:43008
	ds_read_b64_tr_b16 v[178:179], v98 offset:43264
	ds_read_b64_tr_b16 v[180:181], v98 offset:43520
	ds_read_b64_tr_b16 v[182:183], v98 offset:43776
	v_exp_f32_e32 v34, v34
	v_exp_f32_e32 v35, v35
	v_exp_f32_e32 v36, v36
	v_exp_f32_e32 v37, v37
	v_exp_f32_e32 v38, v38
	v_exp_f32_e32 v39, v39
	v_exp_f32_e32 v40, v40
	v_exp_f32_e32 v41, v41
	s_waitcnt lgkmcnt(11)
	v_mfma_f32_32x32x16_bf16 v[50:65], v[106:109], v[66:69], 0
	v_cvt_pk_bf16_f32 v152, v34, v35
	v_cvt_pk_bf16_f32 v153, v36, v37
	v_cvt_pk_bf16_f32 v154, v38, v39
	v_cvt_pk_bf16_f32 v155, v40, v41
	v_add_f32_e32 v115, v34, v115
	v_add_f32_e32 v115, v35, v115
	s_waitcnt lgkmcnt(10)
	v_mfma_f32_32x32x16_bf16 v[50:65], v[110:113], v[70:73], v[50:65]
	v_exp_f32_e32 v42, v42
	v_exp_f32_e32 v43, v43
	v_exp_f32_e32 v44, v44
	v_exp_f32_e32 v45, v45
	v_add_f32_e32 v164, v36, v164
	v_add_f32_e32 v164, v37, v164
	s_waitcnt lgkmcnt(9)
	v_mfma_f32_32x32x16_bf16 v[50:65], v[120:123], v[74:77], v[50:65]
	v_exp_f32_e32 v46, v46
	v_exp_f32_e32 v47, v47
	v_exp_f32_e32 v48, v48
	v_exp_f32_e32 v49, v49
	v_add_f32_e32 v115, v38, v115
	v_add_f32_e32 v115, v39, v115
	s_waitcnt lgkmcnt(8)
	v_mfma_f32_32x32x16_bf16 v[50:65], v[124:127], v[78:81], v[50:65]
	ds_read_b128 v[106:109], v0 offset:4096
	ds_read_b128 v[110:113], v102 offset:4096
	ds_read_b128 v[120:123], v103 offset:4096
	ds_read_b128 v[124:127], v104 offset:4096
	s_waitcnt vmcnt(0)
	ds_write_b128 v100, v[82:85] offset:16384
	ds_write_b128 v165, v[86:89] offset:24576
	s_add_i32 s31, s30, 3
	s_cmp_lt_u32 s31, s96
	s_cbranch_scc0 .Lds1_sk2
	global_load_dwordx4 v[82:85], v[92:93], off offset:1024
	global_load_dwordx4 v[86:89], v[90:91], off offset:1280
	v_lshl_add_u64 v[92:93], v[92:93], 0, s[10:11]
	v_lshl_add_u64 v[90:91], v[90:91], 0, s[10:11]
.Lds1_sk2:
	v_add_f32_e32 v164, v40, v164
	v_add_f32_e32 v164, v41, v164
	s_waitcnt lgkmcnt(12)
	v_mfma_f32_32x32x16_bf16 v[18:33], v[168:171], v[152:155], v[18:33]
	v_cvt_pk_bf16_f32 v156, v42, v43
	v_cvt_pk_bf16_f32 v157, v44, v45
	v_cvt_pk_bf16_f32 v158, v46, v47
	v_cvt_pk_bf16_f32 v159, v48, v49
	v_add_f32_e32 v115, v42, v115
	v_add_f32_e32 v115, v43, v115
	s_waitcnt lgkmcnt(10)
	v_mfma_f32_32x32x16_bf16 v[2:17], v[172:175], v[152:155], v[2:17]
	v_add_f32_e32 v164, v44, v164
	v_add_f32_e32 v164, v45, v164
	v_add_f32_e32 v164, v46, v164
	v_add_f32_e32 v164, v47, v164
	v_add_f32_e32 v164, v48, v164
	v_add_f32_e32 v164, v49, v164
	s_waitcnt lgkmcnt(8)
	v_mfma_f32_32x32x16_bf16 v[18:33], v[176:179], v[156:159], v[18:33]
	v_exp_f32_e32 v136, v136
	v_exp_f32_e32 v137, v137
	v_exp_f32_e32 v138, v138
	v_exp_f32_e32 v139, v139
	s_waitcnt lgkmcnt(6)
	v_mfma_f32_32x32x16_bf16 v[2:17], v[180:183], v[156:159], v[2:17]
	ds_read_b64_tr_b16 v[168:169], v98 offset:45056
	ds_read_b64_tr_b16 v[170:171], v98 offset:45312
	ds_read_b64_tr_b16 v[172:173], v98 offset:45568
	ds_read_b64_tr_b16 v[174:175], v98 offset:45824
	ds_read_b64_tr_b16 v[176:177], v98 offset:47104
	ds_read_b64_tr_b16 v[178:179], v98 offset:47360
	ds_read_b64_tr_b16 v[180:181], v98 offset:47616
	ds_read_b64_tr_b16 v[182:183], v98 offset:47872
	v_exp_f32_e32 v140, v140
	v_exp_f32_e32 v141, v141
	v_exp_f32_e32 v142, v142
	v_exp_f32_e32 v143, v143
	s_waitcnt lgkmcnt(13)
	v_mfma_f32_32x32x16_bf16 v[34:49], v[106:109], v[66:69], 0
	v_cvt_pk_bf16_f32 v160, v136, v137
	v_cvt_pk_bf16_f32 v161, v138, v139
	v_cvt_pk_bf16_f32 v162, v140, v141
	v_cvt_pk_bf16_f32 v163, v142, v143
	v_add_f32_e32 v115, v136, v115
	v_add_f32_e32 v115, v137, v115
	s_waitcnt lgkmcnt(12)
	v_mfma_f32_32x32x16_bf16 v[34:49], v[110:113], v[70:73], v[34:49]
	v_exp_f32_e32 v144, v144
	v_exp_f32_e32 v145, v145
	v_exp_f32_e32 v146, v146
	v_exp_f32_e32 v147, v147
	v_add_f32_e32 v164, v138, v164
	v_add_f32_e32 v164, v139, v164
	s_waitcnt lgkmcnt(11)
	v_mfma_f32_32x32x16_bf16 v[34:49], v[120:123], v[74:77], v[34:49]
	v_exp_f32_e32 v148, v148
	v_exp_f32_e32 v149, v149
	v_exp_f32_e32 v150, v150
	v_exp_f32_e32 v151, v151
	v_add_f32_e32 v115, v140, v115
	v_add_f32_e32 v115, v141, v115
	s_waitcnt lgkmcnt(10)
	v_mfma_f32_32x32x16_bf16 v[34:49], v[124:127], v[78:81], v[34:49]
	v_cvt_pk_bf16_f32 v184, v144, v145
	v_cvt_pk_bf16_f32 v185, v146, v147
	v_cvt_pk_bf16_f32 v186, v148, v149
	v_cvt_pk_bf16_f32 v187, v150, v151
	v_add_f32_e32 v164, v142, v164
	v_add_f32_e32 v164, v143, v164
	s_waitcnt lgkmcnt(6)
	v_mfma_f32_32x32x16_bf16 v[18:33], v[168:171], v[160:163], v[18:33]
	v_add_f32_e32 v115, v144, v115
	v_add_f32_e32 v115, v145, v115
	v_add_f32_e32 v115, v146, v115
	v_add_f32_e32 v115, v147, v115
	s_waitcnt lgkmcnt(4)
	v_mfma_f32_32x32x16_bf16 v[2:17], v[172:175], v[160:163], v[2:17]
	v_add_f32_e32 v164, v148, v164
	v_add_f32_e32 v164, v149, v164
	v_add_f32_e32 v164, v150, v164
	v_add_f32_e32 v164, v151, v164
	s_waitcnt lgkmcnt(2)
	v_mfma_f32_32x32x16_bf16 v[18:33], v[176:179], v[184:187], v[18:33]
	s_waitcnt lgkmcnt(0)
	v_mfma_f32_32x32x16_bf16 v[2:17], v[180:183], v[184:187], v[2:17]
	s_waitcnt lgkmcnt(0)
	s_barrier
	s_add_i32 s30, s30, 1
	s_cmp_ge_u32 s30, s96
	s_cbranch_scc1 .Lds1_done
	s_branch .Lds1_loop
